# v054 + global attention: softmax stabilised with a launch-wide upper bound c on the scores (Cauchy-Schwarz from the q/k RMSNorm gains, stored once per launch) instead of the running row max when c<48:
# speedup vs baseline: 1.0084x; 1.0062x over previous
; #define LAS __attribute__((address_space(3)))
; __global__ void __launch_bounds__(512, 2) mega_fwd(Args a) {
;     ...
;     if (threadIdx.x == 0) ((volatile LAS unsigned*)(lds + LDS_XB))[4] = (__hip_atomic_load((unsigned*)(a.ws + WS_BAR) + XL_BAD, __ATOMIC_RELAXED, __HIP_MEMORY_SCOPE_AGENT) == 0u) ? 1u : 0u;
;     __syncthreads();
;     constexpr int NS = N_PER * NCH;
;     for (int step2 = 0; step2 < 2 * NS; ++step2) {
;         const int step = step2 >> 1;
;         const bool dup_ = ((PH_DUP >> (step % N_PER)) & 1);
;         if ((step2 & 1) && !dup_) continue;
;         STEP_LOCALS
;         const int xl_good = __builtin_amdgcn_readfirstlane((int)((volatile LAS unsigned*)(lds + LDS_XB))[4]);
;         const int xl_x = __builtin_amdgcn_readfirstlane((int)((volatile LAS unsigned*)(lds + LDS_XB))[2]), xl_r = __builtin_amdgcn_readfirstlane((int)((volatile LAS unsigned*)(lds + LDS_XB))[3]);
;         const int cx = xl_good ? (xl_x + 8 * xl_r) : bx;
;         {
;             const int c = step / N_PER, k = step % N_PER;
;             const bool prompt = c < NCH_P;
;     ...
;             const int S_ = prompt ? 8192 : 2048, nseq = CH / S_, NQB = S_ / 256;
;             const int memseq0 = prompt ? (CH / 8192) * c : 8 + (CH / 2048) * (c - NCH_P);
;             gfloat* const ssq1 = ssq; gfloat* const ssq2 = ssq + CH * 4; gfloat* const ssq3 = ssq + 2 * CH * 4;
.LBB0_284:
	s_or_b64 exec, exec, s[0:1]
	s_ashr_i32 s1, s92, 31
	s_lshr_b32 s1, s1, 29
	s_add_i32 s1, s92, s1
	s_ashr_i32 s3, s1, 3
	s_and_b32 s1, s1, -8
	s_ashr_i32 s0, s14, 3
	s_sub_i32 s1, s92, s1
	s_mul_i32 s0, s0, s1
	s_add_i32 s3, s0, s3
	s_ashr_i32 s13, s14, 31
	s_lshl_b32 s50, s14, 1
	s_add_u32 s0, s6, 0x3c58a200
	s_addc_u32 s1, s7, 0
	v_writelane_b32 v254, s0, 4
	v_add_u32_e32 v0, 64, v149
	v_cmp_lt_i32_e32 vcc, v151, v0
	v_writelane_b32 v254, s1, 5
	s_add_u32 s0, s6, 0x3c58a400
	s_addc_u32 s1, s7, 0
	v_writelane_b32 v254, s0, 6
	v_cndmask_b32_e32 v1, v144, v151, vcc
	v_cmp_lt_i32_e32 vcc, v150, v0
	v_writelane_b32 v254, s1, 7
	s_add_u32 s0, s6, 0x3c58a500
	s_addc_u32 s1, s7, 0
	v_writelane_b32 v254, s0, 8
	v_lshlrev_b32_e32 v229, 2, v1
	v_cndmask_b32_e32 v1, v144, v150, vcc
	v_writelane_b32 v254, s1, 9
	s_add_u32 s0, s6, 0x3c58a600
	s_addc_u32 s1, s7, 0
	v_writelane_b32 v254, s0, 10
	v_cmp_lt_i32_e32 vcc, v148, v0
	v_lshlrev_b32_e32 v230, 2, v1
	v_writelane_b32 v254, s1, 11
	s_add_u32 s0, s6, 0x3c58a700
	s_addc_u32 s1, s7, 0
	v_writelane_b32 v254, s0, 12
	v_cndmask_b32_e32 v1, v144, v148, vcc
	v_cmp_lt_i32_e32 vcc, v147, v0
	v_writelane_b32 v254, s1, 13
	s_add_u32 s0, s6, 0x3c58a800
	s_addc_u32 s1, s7, 0
	v_writelane_b32 v254, s0, 14
	v_lshlrev_b32_e32 v231, 2, v1
	v_cndmask_b32_e32 v1, v144, v147, vcc
	v_writelane_b32 v254, s1, 15
	s_add_u32 s0, s6, 0x3c58a900
	s_addc_u32 s1, s7, 0
	v_writelane_b32 v254, s0, 16
	v_lshlrev_b32_e32 v232, 2, v1
	v_cmp_lt_i32_e32 vcc, v146, v0
	v_writelane_b32 v254, s1, 17
	s_add_u32 s0, s6, 0x3c58aa00
	s_addc_u32 s1, s7, 0
	v_writelane_b32 v254, s0, 18
	v_cndmask_b32_e32 v2, v144, v146, vcc
	v_cmp_lt_i32_e32 vcc, v145, v0
	v_writelane_b32 v254, s1, 19
	s_add_u32 s0, s6, 0x3c58ab00
	s_addc_u32 s1, s7, 0
	v_writelane_b32 v254, s0, 20
	v_cndmask_b32_e32 v0, v144, v145, vcc
	v_lshlrev_b32_e32 v234, 2, v0
	v_writelane_b32 v254, s1, 21
	s_add_u32 s0, s6, 0x3c58ac00
	s_addc_u32 s1, s7, 0
	v_writelane_b32 v254, s0, 22
	s_mul_i32 s2, s15, s14
	v_lshlrev_b32_e32 v233, 2, v2
	v_writelane_b32 v254, s1, 23
	s_add_u32 s0, s6, 0x3c58ad00
	s_addc_u32 s1, s7, 0
	v_writelane_b32 v254, s0, 24
	s_mov_b32 s65, 0
	s_movk_i32 s60, 0x100
	v_writelane_b32 v254, s1, 25
	s_add_u32 s0, s6, 0x3c58ae00
	s_addc_u32 s1, s7, 0
	v_writelane_b32 v254, s0, 26
	s_movk_i32 s77, 0x90
	s_movk_i32 s78, 0xffe0
	v_writelane_b32 v254, s1, 27
	s_add_u32 s0, s6, 0x3c58af00
	s_addc_u32 s1, s7, 0
	v_writelane_b32 v254, s0, 28
	v_mov_b32_e32 v235, 0x358637bd
	s_movk_i32 s79, 0x1600
	v_writelane_b32 v254, s1, 29
	s_add_u32 s0, s6, 0x3c58b000
	s_addc_u32 s1, s7, 0
	v_writelane_b32 v254, s0, 30
	s_mov_b32 s22, 0xf800000
	v_mov_b32_e32 v238, 0x260
	v_writelane_b32 v254, s1, 31
	s_add_u32 s0, s6, 0x3c58b100
	s_addc_u32 s1, s7, 0
	v_writelane_b32 v254, s0, 32
	s_movk_i32 s62, 0x110
	v_mov_b32_e32 v241, 0x2000
	v_writelane_b32 v254, s1, 33
	s_add_u32 s0, s6, 0x3c58b200
	s_addc_u32 s1, s7, 0
	v_writelane_b32 v254, s0, 34
	v_mov_b64_e32 v[196:197], 0x200
	v_mov_b64_e32 v[198:199], 0x1ff
	v_writelane_b32 v254, s1, 35
	s_add_u32 s0, s6, 0x3c58b300
	s_addc_u32 s1, s7, 0
	v_writelane_b32 v254, s0, 36
	v_mov_b64_e32 v[250:251], 0xb00
	v_mov_b64_e32 v[202:203], 0xaff
	v_writelane_b32 v254, s1, 37
	s_add_u32 s0, s6, 0x3c58d400
	s_addc_u32 s1, s7, 0
	v_writelane_b32 v254, s0, 38
	v_mov_b32_e32 v239, 0xa0000
	s_mov_b32 s25, 0
	v_writelane_b32 v254, s1, 39
	s_add_u32 s0, s6, 0x3c58d500
	s_addc_u32 s1, s7, 0
	v_writelane_b32 v254, s0, 40
	s_mov_b64 s[68:69], 0x80
	s_mov_b64 s[80:81], 0x20000
	v_writelane_b32 v254, s1, 41
	s_and_b64 s[0:1], s[8:9], exec
	s_cselect_b32 s3, s3, s92
	s_lshl_b32 s0, s3, 3
	s_cmpk_lt_i32 s3, 0x400
	v_writelane_b32 v254, s0, 42
	s_cselect_b64 s[0:1], -1, 0
	v_writelane_b32 v254, s0, 43
	s_cmpk_lt_i32 s3, 0x200
	s_mov_b64 s[82:83], 0x1000
	v_writelane_b32 v254, s1, 44
	s_cselect_b64 s[0:1], -1, 0
	v_writelane_b32 v254, s0, 45
	s_waitcnt lgkmcnt(0)
	s_barrier
; template <int HD, int MODE> ...
;     ...
;     { const gbf16* qrow = Qg + (size_t)(wid * 32 + r32) * q_pitch + hi * 8;
;       u32x4 qraw[HD / 16]; f32x4 gq[HD / 16][2], cs[HD / 16][2];
;       const int pos = q0 + wid * 32 + r32;
; #pragma unroll
;       for (int d0 = 0; d0 < HD / 16; ++d0) { qraw[d0] = *(const gu32x4*)(qrow + d0 * 16);
;           const gf32x4* gp_ = (const gf32x4*)(qgain + 16 * d0 + 8 * hi); gq[d0][0] = gp_[0]; gq[d0][1] = gp_[1];
;           const gf32x4* rp_ = (const gf32x4*)(ropet + ((d0 < HD / 32) ? (pos >> 6) : (pos & 63)) * 16 + 8 * (d0 % (HD / 32)) + 4 * hi); cs[d0][0] = rp_[0]; cs[d0][1] = rp_[1]; }
;       float x[HD / 16][8]; float ss = 0.f;
; #pragma unroll
;       for (int d0 = 0; d0 < HD / 16; ++d0) { const u32x4 v = qraw[d0];
;           x[d0][0] = bflo(v.x); x[d0][1] = bfhi(v.x); x[d0][2] = bflo(v.y); x[d0][3] = bfhi(v.y); x[d0][4] = bflo(v.z); x[d0][5] = bfhi(v.z); x[d0][6] = bflo(v.w); x[d0][7] = bfhi(v.w);
; #pragma unroll
;           for (int e = 0; e < 8; ++e) ss += x[d0][e] * x[d0][e]; }
;       { auto rr = __builtin_amdgcn_permlane32_swap(__float_as_uint(ss), __float_as_uint(ss), false, false); ss = __uint_as_float(rr[0]) + __uint_as_float(rr[1]); }
;       const float rstd = (1.0f / sqrtf(ss * (1.0f / HD) + EPS)) * c;
; __global__ void __launch_bounds__(512, 2) mega_fwd(Args a) {
;     ...
;     constexpr int NS = N_PER * NCH;
;     for (int step2 = 0; step2 < 2 * NS; ++step2) {
;         const int step = step2 >> 1;
;         const bool dup_ = ((PH_DUP >> (step % N_PER)) & 1);
;         if ((step2 & 1) && !dup_) continue;
;         STEP_LOCALS
;         const int xl_good = __builtin_amdgcn_readfirstlane((int)((volatile LAS unsigned*)(lds + LDS_XB))[4]);
;         const int xl_x = __builtin_amdgcn_readfirstlane((int)((volatile LAS unsigned*)(lds + LDS_XB))[2]), xl_r = __builtin_amdgcn_readfirstlane((int)((volatile LAS unsigned*)(lds + LDS_XB))[3]);
;         const int cx = xl_good ? (xl_x + 8 * xl_r) : bx;
;         {
;             const int c = step / N_PER, k = step % N_PER;
;             const bool prompt = c < NCH_P;
;     ...
;             const int S_ = prompt ? 8192 : 2048, nseq = CH / S_, NQB = S_ / 256;
;             const int memseq0 = prompt ? (CH / 8192) * c : 8 + (CH / 2048) * (c - NCH_P);
;             gfloat* const ssq1 = ssq; gfloat* const ssq2 = ssq + CH * 4; gfloat* const ssq3 = ssq + 2 * CH * 4;
	v_writelane_b32 v254, s1, 46
	s_abs_i32 s0, s50
	v_cvt_f32_u32_e32 v1, s0
	s_mul_i32 s1, s2, s33
	v_writelane_b32 v254, s1, 47
	s_sub_i32 s1, 0, s0
	v_rcp_iflag_f32_e32 v1, v1
	s_movk_i32 s33, 0x2800
	v_mul_f32_e32 v0, 0x4f7ffffe, v1
	v_cvt_u32_f32_e32 v0, v0
	v_mov_b32_e32 v1, 0
	v_readfirstlane_b32 s2, v0
	s_mul_i32 s1, s1, s2
	s_mul_hi_u32 s1, s2, s1
	s_add_i32 s2, s2, s1
	s_lshr_b32 s1, s2, 20
	s_mul_i32 s1, s1, s0
	s_sub_i32 s1, 0x1000, s1
	s_sub_i32 s2, s1, s0
	s_cmp_ge_u32 s1, s0
	s_cselect_b32 s1, s2, s1
	s_sub_i32 s2, s1, s0
	s_cmp_ge_u32 s1, s0
	s_cselect_b32 s0, s2, s1
	s_cmp_lg_u32 s0, 0
	s_cselect_b64 s[0:1], -1, 0
	v_writelane_b32 v254, s0, 48
	s_lshl_b32 s12, s14, 4
	s_add_i32 s61, 0, 0x21460
	v_writelane_b32 v254, s1, 49
	s_lshl_b32 s0, s3, 6
	v_writelane_b32 v254, s0, 50
	s_lshl_b32 s0, s14, 6
	v_writelane_b32 v254, s0, 51
	v_writelane_b32 v254, s3, 52
	s_lshl_b32 s0, s3, 7
	v_writelane_b32 v254, s0, 53
	s_add_i32 s0, 0, 0x214b8
	v_writelane_b32 v254, s0, 54
	s_add_i32 s0, 0, 0x21510
	v_writelane_b32 v254, s0, 55
	s_add_i32 s0, 0, 0x21508
	v_writelane_b32 v254, s0, 56
	s_add_i32 s0, 0, 0x2150c
	v_writelane_b32 v254, s0, 57
	s_add_i32 s0, 0, 0x214b0
	v_writelane_b32 v254, s0, 58
	s_add_i32 s0, 0, 0x20000
	v_writelane_b32 v254, s0, 59
	s_add_i32 s0, 0, 0x21450
	v_writelane_b32 v254, s0, 60
	s_add_i32 s0, 0, 0x1b600
	v_writelane_b32 v254, s0, 61
	s_add_i32 s0, 0, 0x21458
	v_writelane_b32 v254, s0, 62
	s_add_i32 s0, 0, 0x21428
	v_writelane_b32 v254, s0, 63
	s_add_i32 s0, 0, 0x21500
	v_writelane_b32 v255, s0, 0
	s_add_i32 s0, 0, 0x21504
	v_writelane_b32 v255, s0, 1
	v_writelane_b32 v255, s92, 2
	v_writelane_b32 v255, s12, 3
	v_writelane_b32 v255, s61, 4
	s_lshl_b32 s19, s14, 7
	s_add_i32 s76, 0, 0x21000
	v_writelane_b32 v255, s50, 5
	v_mov_b32_e32 v246, 0x21450
	ds_read_b128 v[246:249], v246
	v_and_b32_e32 v252, 63, v240
	v_lshlrev_b32_e32 v252, 2, v252
	v_mov_b32_e32 v253, 0
	s_waitcnt lgkmcnt(0)
	v_lshl_add_u64 v[246:247], v[246:247], 0, v[252:253]
	v_lshl_add_u64 v[248:249], v[248:249], 0, v[252:253]
	global_load_dword v246, v[246:247], off
	global_load_dword v248, v[248:249], off
	s_waitcnt vmcnt(0)
	v_and_b32_e32 v246, 0x7fffffff, v246
	v_and_b32_e32 v248, 0x7fffffff, v248
	v_xor_b32_e32 v253, 4, v252
	ds_bpermute_b32 v247, v253, v246
	ds_bpermute_b32 v249, v253, v248
	s_waitcnt lgkmcnt(0)
	v_max_f32_e32 v246, v246, v247
	v_max_f32_e32 v248, v248, v249
	v_xor_b32_e32 v253, 8, v252
	ds_bpermute_b32 v247, v253, v246
	ds_bpermute_b32 v249, v253, v248
	s_waitcnt lgkmcnt(0)
	v_max_f32_e32 v246, v246, v247
	v_max_f32_e32 v248, v248, v249
	v_xor_b32_e32 v253, 16, v252
	ds_bpermute_b32 v247, v253, v246
	ds_bpermute_b32 v249, v253, v248
	s_waitcnt lgkmcnt(0)
	v_max_f32_e32 v246, v246, v247
	v_max_f32_e32 v248, v248, v249
	v_xor_b32_e32 v253, 32, v252
	ds_bpermute_b32 v247, v253, v246
	ds_bpermute_b32 v249, v253, v248
	s_waitcnt lgkmcnt(0)
	v_max_f32_e32 v246, v246, v247
	v_max_f32_e32 v248, v248, v249
	v_xor_b32_e32 v253, 64, v252
	ds_bpermute_b32 v247, v253, v246
	ds_bpermute_b32 v249, v253, v248
	s_waitcnt lgkmcnt(0)
	v_max_f32_e32 v246, v246, v247
	v_max_f32_e32 v248, v248, v249
	v_xor_b32_e32 v253, 128, v252
	ds_bpermute_b32 v247, v253, v246
	ds_bpermute_b32 v249, v253, v248
	s_waitcnt lgkmcnt(0)
	v_max_f32_e32 v246, v246, v247
	v_max_f32_e32 v248, v248, v249
	v_mul_f32_e32 v246, v246, v248
	v_mul_f32_e32 v246, 0x414fbf83, v246
	v_readfirstlane_b32 s0, v246
	v_writelane_b32 v255, s0, 20
	s_branch .LBB0_289

.LBB0_496:
	v_ashrrev_i32_e32 v191, 31, v190
	v_lshlrev_b32_e32 v207, 2, v168
	s_waitcnt lgkmcnt(7)
	v_mfma_f32_32x32x16_bf16 v[66:81], v[162:165], v[130:133], v[34:49]
	v_exp_f32_e32 v65, v98
	v_exp_f32_e32 v162, v99
	s_nop 0
	v_cvt_pk_bf16_f32 v98, v65, v162
	v_add_f32_e32 v65, 0, v65
	v_add_f32_e32 v65, v162, v65
	s_waitcnt lgkmcnt(5)
	v_mfma_f32_32x32x16_bf16 v[34:49], v[158:161], v[130:133], v[34:49]
	v_exp_f32_e32 v158, v100
	v_exp_f32_e32 v159, v101
	v_add_f32_e32 v65, v158, v65
	v_cvt_pk_bf16_f32 v99, v158, v159
	v_add_f32_e32 v65, v159, v65
	v_mfma_f32_32x32x16_bf16 v[66:81], v[154:157], v[134:137], v[66:81]
	v_exp_f32_e32 v154, v102
	v_exp_f32_e32 v155, v103
	v_add_f32_e32 v65, v154, v65
	v_cvt_pk_bf16_f32 v100, v154, v155
	v_add_f32_e32 v65, v155, v65
	s_waitcnt lgkmcnt(3)
	v_mfma_f32_32x32x16_bf16 v[66:81], v[126:129], v[138:141], v[66:81]
	v_exp_f32_e32 v104, v104
	v_exp_f32_e32 v105, v105
	v_add_f32_e32 v65, v104, v65
	v_cvt_pk_bf16_f32 v101, v104, v105
	v_add_f32_e32 v65, v105, v65
	s_waitcnt lgkmcnt(2)
	v_mfma_f32_32x32x16_bf16 v[66:81], v[122:125], v[142:145], v[66:81]
	v_exp_f32_e32 v106, v106
	v_exp_f32_e32 v107, v107
	s_nop 0
	v_cvt_pk_bf16_f32 v102, v106, v107
	v_exp_f32_e32 v108, v108
	v_mfma_f32_32x32x16_bf16 v[34:49], v[60:63], v[134:137], v[34:49]
	v_exp_f32_e32 v109, v109
	v_add_f32_e32 v60, v106, v65
	v_add_f32_e32 v60, v107, v60
	v_add_f32_e32 v60, v108, v60
	v_cvt_pk_bf16_f32 v103, v108, v109
	v_exp_f32_e32 v110, v110
	v_exp_f32_e32 v111, v111
	s_waitcnt lgkmcnt(1)
	v_mfma_f32_32x32x16_bf16 v[34:49], v[56:59], v[138:141], v[34:49]
	v_add_f32_e32 v60, v109, v60
	v_add_f32_e32 v60, v110, v60
	v_cvt_pk_bf16_f32 v104, v110, v111
	v_exp_f32_e32 v112, v112
	v_exp_f32_e32 v162, v113
	v_add_f32_e32 v60, v111, v60
	v_add_f32_e32 v65, v112, v60
	v_cvt_pk_bf16_f32 v105, v112, v162
	s_setprio 0
	ds_read_b128 v[56:59], v64 offset:27648
	ds_read_b128 v[60:63], v64 offset:27680
	ds_read_b128 v[106:109], v64 offset:27712
	ds_read_b128 v[110:113], v64 offset:27744
	ds_read_b128 v[122:125], v64 offset:32256
	ds_read_b128 v[126:129], v64 offset:32288
	ds_read_b128 v[154:157], v64 offset:32320
	ds_read_b128 v[158:161], v64 offset:32352
	v_add_f32_e32 v64, v162, v65
	v_exp_f32_e32 v65, v82
	v_exp_f32_e32 v82, v83
	v_exp_f32_e32 v83, v84
	v_exp_f32_e32 v84, v85
	v_add_f32_e32 v64, v65, v64
	v_exp_f32_e32 v85, v86
	v_add_f32_e32 v64, v82, v64
	v_exp_f32_e32 v86, v87
	v_add_f32_e32 v64, v83, v64
	v_exp_f32_e32 v87, v88
	v_add_f32_e32 v64, v84, v64
	v_exp_f32_e32 v88, v89
	v_add_f32_e32 v64, v85, v64
	v_exp_f32_e32 v89, v90
	v_add_f32_e32 v64, v86, v64
	v_exp_f32_e32 v90, v91
	v_add_f32_e32 v64, v87, v64
	v_exp_f32_e32 v91, v92
	v_add_f32_e32 v64, v88, v64
	v_exp_f32_e32 v92, v93
	v_add_f32_e32 v64, v89, v64
	v_exp_f32_e32 v93, v94
	v_add_f32_e32 v64, v90, v64
	v_exp_f32_e32 v94, v95
	v_add_f32_e32 v64, v91, v64
	v_exp_f32_e32 v95, v96
	v_add_f32_e32 v64, v92, v64
	v_exp_f32_e32 v96, v97
	v_add_f32_e32 v64, v93, v64
	v_add_f32_e32 v64, v94, v64
	v_add_f32_e32 v64, v95, v64
	v_add_f32_e32 v64, v96, v64
	v_cvt_pk_bf16_f32 v82, v65, v82
	v_cvt_pk_bf16_f32 v83, v83, v84
	v_cvt_pk_bf16_f32 v84, v85, v86
	v_cvt_pk_bf16_f32 v85, v87, v88
	v_cvt_pk_bf16_f32 v86, v89, v90
	v_cvt_pk_bf16_f32 v87, v91, v92
	v_cvt_pk_bf16_f32 v88, v93, v94
	v_cvt_pk_bf16_f32 v89, v95, v96
	s_setprio 1
	s_waitcnt lgkmcnt(7)
	v_mfma_f32_32x32x16_bf16 v[18:33], v[56:59], v[98:101], v[18:33]
	v_add_f32_e32 v210, v50, v64
	s_waitcnt lgkmcnt(3)
	v_mfma_f32_32x32x16_bf16 v[2:17], v[122:125], v[98:101], v[2:17]
	v_mfma_f32_32x32x16_bf16 v[18:33], v[60:63], v[102:105], v[18:33]
	s_waitcnt lgkmcnt(2)
	v_mfma_f32_32x32x16_bf16 v[2:17], v[126:129], v[102:105], v[2:17]
	v_mfma_f32_32x32x16_bf16 v[18:33], v[106:109], v[82:85], v[18:33]
	s_waitcnt lgkmcnt(1)
	v_mfma_f32_32x32x16_bf16 v[2:17], v[154:157], v[82:85], v[2:17]
	v_mfma_f32_32x32x16_bf16 v[18:33], v[110:113], v[86:89], v[18:33]
	s_waitcnt lgkmcnt(0)
	v_mfma_f32_32x32x16_bf16 v[2:17], v[158:161], v[86:89], v[2:17]
	v_mfma_f32_32x32x16_bf16 v[34:49], v[52:55], v[142:145], v[34:49]
	s_setprio 0
	s_movk_i32 s2, 0x4800
	s_mov_b32 s3, 0
	s_mov_b32 s0, 0x9000
	s_mov_b32 s10, 6
	v_mov_b32_e32 v50, v51
	v_mov_b32_e32 v52, v51
	v_mov_b32_e32 v53, v51
	v_mov_b32_e32 v54, v51
	v_mov_b32_e32 v55, v51
	v_mov_b32_e32 v56, v51
	v_mov_b32_e32 v57, v51
	v_mov_b32_e32 v58, v51
	v_mov_b32_e32 v59, v51
	v_mov_b32_e32 v60, v51
	v_mov_b32_e32 v61, v51
	v_mov_b32_e32 v62, v51
	v_mov_b32_e32 v63, v51
	v_mov_b32_e32 v64, v51
	v_mov_b32_e32 v65, v51
	s_waitcnt vmcnt(3)
	ds_write_b128 v169, v[114:117]
	s_waitcnt vmcnt(2)
	ds_write_b128 v170, v[118:121] offset:9216
	v_readlane_b32 s1, v255, 20
	s_cmp_lt_u32 s1, 0x42400000
	s_cbranch_scc0 .Lattn_online_pre
	v_sub_f32_e32 v50, s1, v206
	v_exp_f32_e64 v52, -v50
	v_mov_b32_e32 v206, s1
	v_pk_add_f32 v[66:67], v[66:67], v[50:51] op_sel_hi:[1,0] neg_lo:[0,1] neg_hi:[0,1]
	v_pk_add_f32 v[68:69], v[68:69], v[50:51] op_sel_hi:[1,0] neg_lo:[0,1] neg_hi:[0,1]
	v_pk_add_f32 v[70:71], v[70:71], v[50:51] op_sel_hi:[1,0] neg_lo:[0,1] neg_hi:[0,1]
	v_pk_add_f32 v[72:73], v[72:73], v[50:51] op_sel_hi:[1,0] neg_lo:[0,1] neg_hi:[0,1]
	v_pk_add_f32 v[74:75], v[74:75], v[50:51] op_sel_hi:[1,0] neg_lo:[0,1] neg_hi:[0,1]
	v_pk_add_f32 v[76:77], v[76:77], v[50:51] op_sel_hi:[1,0] neg_lo:[0,1] neg_hi:[0,1]
	v_pk_add_f32 v[78:79], v[78:79], v[50:51] op_sel_hi:[1,0] neg_lo:[0,1] neg_hi:[0,1]
	v_pk_add_f32 v[80:81], v[80:81], v[50:51] op_sel_hi:[1,0] neg_lo:[0,1] neg_hi:[0,1]
	v_pk_add_f32 v[34:35], v[34:35], v[50:51] op_sel_hi:[1,0] neg_lo:[0,1] neg_hi:[0,1]
	v_pk_add_f32 v[36:37], v[36:37], v[50:51] op_sel_hi:[1,0] neg_lo:[0,1] neg_hi:[0,1]
	v_pk_add_f32 v[38:39], v[38:39], v[50:51] op_sel_hi:[1,0] neg_lo:[0,1] neg_hi:[0,1]
	v_pk_add_f32 v[40:41], v[40:41], v[50:51] op_sel_hi:[1,0] neg_lo:[0,1] neg_hi:[0,1]
	v_pk_add_f32 v[42:43], v[42:43], v[50:51] op_sel_hi:[1,0] neg_lo:[0,1] neg_hi:[0,1]
	v_pk_add_f32 v[44:45], v[44:45], v[50:51] op_sel_hi:[1,0] neg_lo:[0,1] neg_hi:[0,1]
	v_pk_add_f32 v[46:47], v[46:47], v[50:51] op_sel_hi:[1,0] neg_lo:[0,1] neg_hi:[0,1]
	v_pk_add_f32 v[48:49], v[48:49], v[50:51] op_sel_hi:[1,0] neg_lo:[0,1] neg_hi:[0,1]
	v_pk_mul_f32 v[2:3], v[2:3], v[52:53] op_sel_hi:[1,0]
	v_pk_mul_f32 v[4:5], v[4:5], v[52:53] op_sel_hi:[1,0]
	v_pk_mul_f32 v[6:7], v[6:7], v[52:53] op_sel_hi:[1,0]
	v_pk_mul_f32 v[8:9], v[8:9], v[52:53] op_sel_hi:[1,0]
	v_pk_mul_f32 v[10:11], v[10:11], v[52:53] op_sel_hi:[1,0]
	v_pk_mul_f32 v[12:13], v[12:13], v[52:53] op_sel_hi:[1,0]
	v_pk_mul_f32 v[14:15], v[14:15], v[52:53] op_sel_hi:[1,0]
	v_pk_mul_f32 v[16:17], v[16:17], v[52:53] op_sel_hi:[1,0]
	v_pk_mul_f32 v[18:19], v[18:19], v[52:53] op_sel_hi:[1,0]
	v_pk_mul_f32 v[20:21], v[20:21], v[52:53] op_sel_hi:[1,0]
	v_pk_mul_f32 v[22:23], v[22:23], v[52:53] op_sel_hi:[1,0]
	v_pk_mul_f32 v[24:25], v[24:25], v[52:53] op_sel_hi:[1,0]
	v_pk_mul_f32 v[26:27], v[26:27], v[52:53] op_sel_hi:[1,0]
	v_pk_mul_f32 v[28:29], v[28:29], v[52:53] op_sel_hi:[1,0]
	v_pk_mul_f32 v[30:31], v[30:31], v[52:53] op_sel_hi:[1,0]
	v_pk_mul_f32 v[32:33], v[32:33], v[52:53] op_sel_hi:[1,0]
	v_mul_f32_e32 v210, v210, v52
	v_xor_b32_e32 v50, 0x80000000, v206
	v_mov_b32_e32 v51, v50
	v_mov_b32_e32 v52, v50
	v_mov_b32_e32 v53, v50
	v_mov_b32_e32 v54, v50
	v_mov_b32_e32 v55, v50
	v_mov_b32_e32 v56, v50
	v_mov_b32_e32 v57, v50
	v_mov_b32_e32 v58, v50
	v_mov_b32_e32 v59, v50
	v_mov_b32_e32 v60, v50
	v_mov_b32_e32 v61, v50
	v_mov_b32_e32 v62, v50
	v_mov_b32_e32 v63, v50
	v_mov_b32_e32 v64, v50
	v_mov_b32_e32 v65, v50
.Lattn_fx_top:
	s_add_i32 s11, s10, -1
	s_min_i32 s1, s11, s58
	s_lshl_b32 s44, s1, 6
	s_ashr_i32 s45, s44, 31
	v_mad_i64_i32 v[200:201], s[46:47], s1, v239, v[194:195]
	v_lshl_add_u64 v[236:237], s[44:45], 1, v[208:209]
	s_mov_b32 s12, s3
	s_mov_b32 s3, s0
	s_add_i32 s15, s12, 0
	s_add_i32 s24, s10, -2
	s_cmp_lt_u32 s24, s16
	s_cselect_b64 s[0:1], -1, 0
	s_add_i32 s23, s3, 0
	s_waitcnt lgkmcnt(0)
	s_barrier
	v_add_u32_e32 v252, s15, v193
	ds_read_b128 v[162:165], v252
	ds_read_b128 v[178:181], v252 offset:4608
	ds_read_b128 v[166:169], v252 offset:32
	ds_read_b128 v[182:185], v252 offset:4640
	ds_read_b128 v[170:173], v252 offset:64
	ds_read_b128 v[186:189], v252 offset:4672
	ds_read_b128 v[174:177], v252 offset:96
	ds_read_b128 v[82:85], v252 offset:4704
	global_load_dwordx4 v[154:157], v[200:201], off offset:1024
	global_load_dwordx4 v[158:161], v[236:237], off
	v_add_u32_e32 v253, s23, v0
	v_exp_f32_e32 v66, v66
	v_exp_f32_e32 v67, v67
	v_exp_f32_e32 v68, v68
	v_exp_f32_e32 v69, v69
	v_add_f32_e32 v246, v66, v67
	v_cvt_pk_bf16_f32 v66, v66, v67
	s_waitcnt lgkmcnt(7)
	v_mfma_f32_32x32x16_bf16 v[114:129], v[162:165], v[130:133], v[50:65]
	ds_read_b128 v[86:89], v253 offset:9216
	ds_read_b128 v[216:219], v253 offset:13824
	v_exp_f32_e32 v70, v70
	v_exp_f32_e32 v71, v71
	v_add_f32_e32 v246, v68, v246
	v_add_f32_e32 v246, v69, v246
	v_cvt_pk_bf16_f32 v67, v68, v69
	s_waitcnt lgkmcnt(8)
	v_mfma_f32_32x32x16_bf16 v[98:113], v[178:181], v[130:133], v[50:65]
	ds_read_b128 v[90:93], v253 offset:9248
	ds_read_b128 v[220:223], v253 offset:13856
	v_exp_f32_e32 v72, v72
	v_exp_f32_e32 v73, v73
	v_add_f32_e32 v246, v70, v246
	v_add_f32_e32 v246, v71, v246
	v_cvt_pk_bf16_f32 v68, v70, v71
	s_waitcnt lgkmcnt(9)
	v_mfma_f32_32x32x16_bf16 v[114:129], v[166:169], v[134:137], v[114:129]
	ds_read_b128 v[94:97], v253 offset:9280
	ds_read_b128 v[224:227], v253 offset:13888
	v_exp_f32_e32 v74, v74
	v_exp_f32_e32 v75, v75
	v_add_f32_e32 v246, v72, v246
	v_add_f32_e32 v246, v73, v246
	v_cvt_pk_bf16_f32 v69, v72, v73
	s_waitcnt lgkmcnt(10)
	v_mfma_f32_32x32x16_bf16 v[98:113], v[182:185], v[134:137], v[98:113]
	ds_read_b128 v[212:215], v253 offset:9312
	ds_read_b128 v[242:245], v253 offset:13920
	v_exp_f32_e32 v76, v76
	v_exp_f32_e32 v77, v77
	v_add_f32_e32 v246, v74, v246
	v_add_f32_e32 v246, v75, v246
	v_cvt_pk_bf16_f32 v70, v74, v75
	s_waitcnt lgkmcnt(11)
	v_mfma_f32_32x32x16_bf16 v[114:129], v[170:173], v[138:141], v[114:129]
	v_exp_f32_e32 v78, v78
	v_exp_f32_e32 v79, v79
	v_add_f32_e32 v246, v76, v246
	v_add_f32_e32 v246, v77, v246
	v_cvt_pk_bf16_f32 v71, v76, v77
	s_waitcnt lgkmcnt(10)
	v_mfma_f32_32x32x16_bf16 v[98:113], v[186:189], v[138:141], v[98:113]
	v_exp_f32_e32 v80, v80
	v_exp_f32_e32 v81, v81
	v_add_f32_e32 v246, v78, v246
	v_add_f32_e32 v246, v79, v246
	v_cvt_pk_bf16_f32 v72, v78, v79
	s_waitcnt lgkmcnt(9)
	v_mfma_f32_32x32x16_bf16 v[114:129], v[174:177], v[142:145], v[114:129]
	v_exp_f32_e32 v34, v34
	v_exp_f32_e32 v35, v35
	v_add_f32_e32 v246, v80, v246
	v_add_f32_e32 v246, v81, v246
	v_cvt_pk_bf16_f32 v73, v80, v81
	s_waitcnt lgkmcnt(8)
	v_mfma_f32_32x32x16_bf16 v[98:113], v[82:85], v[142:145], v[98:113]
	v_exp_f32_e32 v36, v36
	v_exp_f32_e32 v37, v37
	v_add_f32_e32 v247, v34, v35
	v_cvt_pk_bf16_f32 v74, v34, v35
	s_waitcnt lgkmcnt(7)
	v_mfma_f32_32x32x16_bf16 v[18:33], v[86:89], v[66:69], v[18:33]
	v_exp_f32_e32 v38, v38
	v_exp_f32_e32 v39, v39
	v_add_f32_e32 v247, v36, v247
	v_add_f32_e32 v247, v37, v247
	v_cvt_pk_bf16_f32 v75, v36, v37
	s_waitcnt lgkmcnt(6)
	v_mfma_f32_32x32x16_bf16 v[2:17], v[216:219], v[66:69], v[2:17]
	v_exp_f32_e32 v40, v40
	v_exp_f32_e32 v41, v41
	v_add_f32_e32 v247, v38, v247
	v_add_f32_e32 v247, v39, v247
	v_cvt_pk_bf16_f32 v76, v38, v39
	s_waitcnt lgkmcnt(5)
	v_mfma_f32_32x32x16_bf16 v[18:33], v[90:93], v[70:73], v[18:33]
	v_exp_f32_e32 v42, v42
	v_exp_f32_e32 v43, v43
	v_add_f32_e32 v247, v40, v247
	v_add_f32_e32 v247, v41, v247
	v_cvt_pk_bf16_f32 v77, v40, v41
	s_waitcnt lgkmcnt(4)
	v_mfma_f32_32x32x16_bf16 v[2:17], v[220:223], v[70:73], v[2:17]
	v_exp_f32_e32 v44, v44
	v_exp_f32_e32 v45, v45
	v_add_f32_e32 v247, v42, v247
	v_add_f32_e32 v247, v43, v247
	v_cvt_pk_bf16_f32 v78, v42, v43
	s_waitcnt lgkmcnt(3)
	v_mfma_f32_32x32x16_bf16 v[18:33], v[94:97], v[74:77], v[18:33]
	v_exp_f32_e32 v46, v46
	v_exp_f32_e32 v47, v47
	v_add_f32_e32 v247, v44, v247
	v_add_f32_e32 v247, v45, v247
	v_cvt_pk_bf16_f32 v79, v44, v45
	s_waitcnt lgkmcnt(2)
	v_mfma_f32_32x32x16_bf16 v[2:17], v[224:227], v[74:77], v[2:17]
	v_exp_f32_e32 v48, v48
	v_exp_f32_e32 v49, v49
	v_add_f32_e32 v247, v46, v247
	v_add_f32_e32 v247, v47, v247
	v_cvt_pk_bf16_f32 v80, v46, v47
	v_add_f32_e32 v247, v48, v247
	v_add_f32_e32 v247, v49, v247
	v_cvt_pk_bf16_f32 v81, v48, v49
	s_waitcnt lgkmcnt(1)
	v_mfma_f32_32x32x16_bf16 v[18:33], v[212:215], v[78:81], v[18:33]
	s_waitcnt lgkmcnt(0)
	v_mfma_f32_32x32x16_bf16 v[2:17], v[242:245], v[78:81], v[2:17]
	v_add_f32_e32 v210, v210, v246
	v_add_f32_e32 v210, v210, v247
	s_cmp_ge_u32 s24, s16
	s_cbranch_scc1 .Lattn_fx_skipw1
	s_add_i32 s24, s2, 0
	v_add_u32_e32 v200, s24, v192
	v_add_u32_e32 v201, s24, v204
	s_waitcnt vmcnt(3)
	ds_write_b128 v200, v[146:149]
	s_waitcnt vmcnt(2)
	ds_write_b128 v201, v[150:153] offset:9216
.Lattn_fx_skipw1:
	s_min_i32 s24, s10, s58
	s_lshl_b32 s44, s24, 6
	s_ashr_i32 s45, s44, 31
	v_mad_i64_i32 v[200:201], s[46:47], s24, v239, v[194:195]
	v_lshl_add_u64 v[236:237], s[44:45], 1, v[208:209]
	s_waitcnt lgkmcnt(0)
	s_barrier
	v_add_u32_e32 v252, s2, v205
	ds_read_b128 v[162:165], v252
	ds_read_b128 v[178:181], v252 offset:4608
	ds_read_b128 v[166:169], v252 offset:32
	ds_read_b128 v[182:185], v252 offset:4640
	ds_read_b128 v[170:173], v252 offset:64
	ds_read_b128 v[186:189], v252 offset:4672
	ds_read_b128 v[174:177], v252 offset:96
	ds_read_b128 v[82:85], v252 offset:4704
	global_load_dwordx4 v[146:149], v[200:201], off offset:1024
	global_load_dwordx4 v[150:153], v[236:237], off
	v_add_u32_e32 v253, s15, v0
	v_exp_f32_e32 v114, v114
	v_exp_f32_e32 v115, v115
	v_exp_f32_e32 v116, v116
	v_exp_f32_e32 v117, v117
	v_add_f32_e32 v246, v114, v115
	v_cvt_pk_bf16_f32 v114, v114, v115
	s_waitcnt lgkmcnt(7)
	v_mfma_f32_32x32x16_bf16 v[66:81], v[162:165], v[130:133], v[50:65]
	ds_read_b128 v[86:89], v253 offset:9216
	ds_read_b128 v[216:219], v253 offset:13824
	v_exp_f32_e32 v118, v118
	v_exp_f32_e32 v119, v119
	v_add_f32_e32 v246, v116, v246
	v_add_f32_e32 v246, v117, v246
	v_cvt_pk_bf16_f32 v115, v116, v117
	s_waitcnt lgkmcnt(8)
	v_mfma_f32_32x32x16_bf16 v[34:49], v[178:181], v[130:133], v[50:65]
	ds_read_b128 v[90:93], v253 offset:9248
	ds_read_b128 v[220:223], v253 offset:13856
	v_exp_f32_e32 v120, v120
	v_exp_f32_e32 v121, v121
	v_add_f32_e32 v246, v118, v246
	v_add_f32_e32 v246, v119, v246
	v_cvt_pk_bf16_f32 v116, v118, v119
	s_waitcnt lgkmcnt(9)
	v_mfma_f32_32x32x16_bf16 v[66:81], v[166:169], v[134:137], v[66:81]
	ds_read_b128 v[94:97], v253 offset:9280
	ds_read_b128 v[224:227], v253 offset:13888
	v_exp_f32_e32 v122, v122
	v_exp_f32_e32 v123, v123
	v_add_f32_e32 v246, v120, v246
	v_add_f32_e32 v246, v121, v246
	v_cvt_pk_bf16_f32 v117, v120, v121
	s_waitcnt lgkmcnt(10)
	v_mfma_f32_32x32x16_bf16 v[34:49], v[182:185], v[134:137], v[34:49]
	ds_read_b128 v[212:215], v253 offset:9312
	ds_read_b128 v[242:245], v253 offset:13920
	v_exp_f32_e32 v124, v124
	v_exp_f32_e32 v125, v125
	v_add_f32_e32 v246, v122, v246
	v_add_f32_e32 v246, v123, v246
	v_cvt_pk_bf16_f32 v118, v122, v123
	s_waitcnt lgkmcnt(11)
	v_mfma_f32_32x32x16_bf16 v[66:81], v[170:173], v[138:141], v[66:81]
	v_exp_f32_e32 v126, v126
	v_exp_f32_e32 v127, v127
	v_add_f32_e32 v246, v124, v246
	v_add_f32_e32 v246, v125, v246
	v_cvt_pk_bf16_f32 v119, v124, v125
	s_waitcnt lgkmcnt(10)
	v_mfma_f32_32x32x16_bf16 v[34:49], v[186:189], v[138:141], v[34:49]
	v_exp_f32_e32 v128, v128
	v_exp_f32_e32 v129, v129
	v_add_f32_e32 v246, v126, v246
	v_add_f32_e32 v246, v127, v246
	v_cvt_pk_bf16_f32 v120, v126, v127
	s_waitcnt lgkmcnt(9)
	v_mfma_f32_32x32x16_bf16 v[66:81], v[174:177], v[142:145], v[66:81]
	v_exp_f32_e32 v98, v98
	v_exp_f32_e32 v99, v99
	v_add_f32_e32 v246, v128, v246
	v_add_f32_e32 v246, v129, v246
	v_cvt_pk_bf16_f32 v121, v128, v129
	s_waitcnt lgkmcnt(8)
	v_mfma_f32_32x32x16_bf16 v[34:49], v[82:85], v[142:145], v[34:49]
	v_exp_f32_e32 v100, v100
	v_exp_f32_e32 v101, v101
	v_add_f32_e32 v247, v98, v99
	v_cvt_pk_bf16_f32 v122, v98, v99
	s_waitcnt lgkmcnt(7)
	v_mfma_f32_32x32x16_bf16 v[18:33], v[86:89], v[114:117], v[18:33]
	v_exp_f32_e32 v102, v102
	v_exp_f32_e32 v103, v103
	v_add_f32_e32 v247, v100, v247
	v_add_f32_e32 v247, v101, v247
	v_cvt_pk_bf16_f32 v123, v100, v101
	s_waitcnt lgkmcnt(6)
	v_mfma_f32_32x32x16_bf16 v[2:17], v[216:219], v[114:117], v[2:17]
	v_exp_f32_e32 v104, v104
	v_exp_f32_e32 v105, v105
	v_add_f32_e32 v247, v102, v247
	v_add_f32_e32 v247, v103, v247
	v_cvt_pk_bf16_f32 v124, v102, v103
	s_waitcnt lgkmcnt(5)
	v_mfma_f32_32x32x16_bf16 v[18:33], v[90:93], v[118:121], v[18:33]
	v_exp_f32_e32 v106, v106
	v_exp_f32_e32 v107, v107
	v_add_f32_e32 v247, v104, v247
	v_add_f32_e32 v247, v105, v247
	v_cvt_pk_bf16_f32 v125, v104, v105
	s_waitcnt lgkmcnt(4)
	v_mfma_f32_32x32x16_bf16 v[2:17], v[220:223], v[118:121], v[2:17]
	v_exp_f32_e32 v108, v108
	v_exp_f32_e32 v109, v109
	v_add_f32_e32 v247, v106, v247
	v_add_f32_e32 v247, v107, v247
	v_cvt_pk_bf16_f32 v126, v106, v107
	s_waitcnt lgkmcnt(3)
	v_mfma_f32_32x32x16_bf16 v[18:33], v[94:97], v[122:125], v[18:33]
	v_exp_f32_e32 v110, v110
	v_exp_f32_e32 v111, v111
	v_add_f32_e32 v247, v108, v247
	v_add_f32_e32 v247, v109, v247
	v_cvt_pk_bf16_f32 v127, v108, v109
	s_waitcnt lgkmcnt(2)
	v_mfma_f32_32x32x16_bf16 v[2:17], v[224:227], v[122:125], v[2:17]
	v_exp_f32_e32 v112, v112
	v_exp_f32_e32 v113, v113
	v_add_f32_e32 v247, v110, v247
	v_add_f32_e32 v247, v111, v247
	v_cvt_pk_bf16_f32 v128, v110, v111
	v_add_f32_e32 v247, v112, v247
	v_add_f32_e32 v247, v113, v247
	v_cvt_pk_bf16_f32 v129, v112, v113
	s_waitcnt lgkmcnt(1)
	v_mfma_f32_32x32x16_bf16 v[18:33], v[212:215], v[126:129], v[18:33]
	s_waitcnt lgkmcnt(0)
	v_mfma_f32_32x32x16_bf16 v[2:17], v[242:245], v[126:129], v[2:17]
	v_add_f32_e32 v210, v210, v246
	v_add_f32_e32 v210, v210, v247
	s_cmp_ge_u32 s11, s16
	s_cbranch_scc1 .Lattn_fx_skipw2
	v_add_u32_e32 v200, s23, v192
	v_add_u32_e32 v201, s23, v204
	s_waitcnt vmcnt(3)
	ds_write_b128 v200, v[154:157]
	s_waitcnt vmcnt(2)
	ds_write_b128 v201, v[158:161] offset:9216

.Lattn_online_pre:
	v_max3_f32 v248, v66, v67, v68
	v_max3_f32 v249, v34, v35, v36
	v_max3_f32 v248, v248, v69, v70
	v_max3_f32 v249, v249, v37, v38
	v_max3_f32 v248, v248, v71, v72
	v_max3_f32 v249, v249, v39, v40
	v_max3_f32 v248, v248, v73, v74
	v_max3_f32 v249, v249, v41, v42
	v_max3_f32 v248, v248, v75, v76
	v_max3_f32 v249, v249, v43, v44
	v_max3_f32 v248, v248, v77, v78
	v_max3_f32 v249, v249, v45, v46
	v_max3_f32 v248, v248, v79, v80
	v_max3_f32 v249, v249, v47, v48
	v_max_f32_e32 v248, v248, v81
	v_max_f32_e32 v249, v249, v49
	v_max_f32_e32 v248, v248, v249
	v_mov_b32_e32 v211, v248
	s_nop 1
	v_permlane32_swap_b32_e32 v248, v211
	v_max_f32_e32 v248, v248, v211
	v_cmp_lt_f32_e32 vcc, 4.0, v248
	s_cbranch_vccnz .Lattn_resc_pre
